# scan x-prefetch fast path (19 unguarded loads when the chunk is interior) + MLA tile-load addressing folded to per-lane pointers and strides
# speedup vs baseline: 1.0724x; 1.0173x over previous
.LBB0_555:
	s_waitcnt vmcnt(0)
	v_lshlrev_b32_e32 v64, 16, v103
	v_lshlrev_b32_e32 v65, 16, v102
	v_fma_f32 v64, v95, v64, v97
	v_lshlrev_b32_e32 v66, 16, v105
	v_fmac_f32_e32 v64, v89, v65
	v_lshlrev_b32_e32 v67, 16, v104
	v_fmac_f32_e32 v64, v94, v66
	v_fmac_f32_e32 v64, v96, v67
	v_cvt_pk_bf16_f32 v64, v64, s0
	ds_write_b16 v168, v64
	v_fma_f32 v64, v95, v65, v97
	v_fmac_f32_e32 v64, v89, v66
	v_lshlrev_b32_e32 v68, 16, v107
	v_fmac_f32_e32 v64, v94, v67
	v_fmac_f32_e32 v64, v96, v68
	v_cvt_pk_bf16_f32 v64, v64, s0
	ds_write_b16 v168, v64 offset:272
	v_fma_f32 v64, v95, v66, v97
	v_fmac_f32_e32 v64, v89, v67
	v_lshlrev_b32_e32 v69, 16, v106
	v_fmac_f32_e32 v64, v94, v68
	v_fmac_f32_e32 v64, v96, v69
	v_cvt_pk_bf16_f32 v64, v64, s0
	ds_write_b16 v168, v64 offset:544
	v_fma_f32 v64, v95, v67, v97
	v_fmac_f32_e32 v64, v89, v68
	v_lshlrev_b32_e32 v70, 16, v123
	v_fmac_f32_e32 v64, v94, v69
	v_fmac_f32_e32 v64, v96, v70
	v_cvt_pk_bf16_f32 v64, v64, s0
	ds_write_b16 v168, v64 offset:816
	v_fma_f32 v64, v95, v68, v97
	v_fmac_f32_e32 v64, v89, v69
	v_lshlrev_b32_e32 v71, 16, v122
	v_fmac_f32_e32 v64, v94, v70
	v_fmac_f32_e32 v64, v96, v71
	v_cvt_pk_bf16_f32 v64, v64, s0
	ds_write_b16 v168, v64 offset:1088
	v_fma_f32 v64, v95, v69, v97
	v_fmac_f32_e32 v64, v89, v70
	v_lshlrev_b32_e32 v72, 16, v125
	v_fmac_f32_e32 v64, v94, v71
	v_fmac_f32_e32 v64, v96, v72
	v_cvt_pk_bf16_f32 v64, v64, s0
	ds_write_b16 v168, v64 offset:1360
	v_fma_f32 v64, v95, v70, v97
	v_fmac_f32_e32 v64, v89, v71
	v_lshlrev_b32_e32 v73, 16, v124
	v_fmac_f32_e32 v64, v94, v72
	v_fmac_f32_e32 v64, v96, v73
	v_cvt_pk_bf16_f32 v64, v64, s0
	ds_write_b16 v168, v64 offset:1632
	v_fma_f32 v64, v95, v71, v97
	v_fmac_f32_e32 v64, v89, v72
	v_lshlrev_b32_e32 v74, 16, v128
	v_fmac_f32_e32 v64, v94, v73
	v_fmac_f32_e32 v64, v96, v74
	v_cvt_pk_bf16_f32 v64, v64, s0
	ds_write_b16 v168, v64 offset:1904
	v_fma_f32 v64, v95, v72, v97
	v_fmac_f32_e32 v64, v89, v73
	v_lshlrev_b32_e32 v75, 16, v127
	v_fmac_f32_e32 v64, v94, v74
	v_fmac_f32_e32 v64, v96, v75
	v_cvt_pk_bf16_f32 v64, v64, s0
	ds_write_b16 v168, v64 offset:2176
	v_fma_f32 v64, v95, v73, v97
	v_fmac_f32_e32 v64, v89, v74
	v_lshlrev_b32_e32 v76, 16, v130
	v_fmac_f32_e32 v64, v94, v75
	v_fmac_f32_e32 v64, v96, v76
	v_cvt_pk_bf16_f32 v64, v64, s0
	ds_write_b16 v168, v64 offset:2448
	v_fma_f32 v64, v95, v74, v97
	v_fmac_f32_e32 v64, v89, v75
	v_lshlrev_b32_e32 v77, 16, v129
	v_fmac_f32_e32 v64, v94, v76
	v_fmac_f32_e32 v64, v96, v77
	v_cvt_pk_bf16_f32 v64, v64, s0
	ds_write_b16 v168, v64 offset:2720
	v_fma_f32 v64, v95, v75, v97
	v_fmac_f32_e32 v64, v89, v76
	v_lshlrev_b32_e32 v78, 16, v171
	v_fmac_f32_e32 v64, v94, v77
	v_fmac_f32_e32 v64, v96, v78
	v_cvt_pk_bf16_f32 v64, v64, s0
	ds_write_b16 v168, v64 offset:2992
	v_fma_f32 v64, v95, v76, v97
	v_fmac_f32_e32 v64, v89, v77
	v_lshlrev_b32_e32 v79, 16, v170
	v_fmac_f32_e32 v64, v94, v78
	v_fmac_f32_e32 v64, v96, v79
	v_cvt_pk_bf16_f32 v64, v64, s0
	ds_write_b16 v168, v64 offset:3264
	v_fma_f32 v64, v95, v77, v97
	v_fmac_f32_e32 v64, v89, v78
	v_lshlrev_b32_e32 v80, 16, v173
	v_fmac_f32_e32 v64, v94, v79
	v_fmac_f32_e32 v64, v96, v80
	v_cvt_pk_bf16_f32 v64, v64, s0
	ds_write_b16 v168, v64 offset:3536
	v_fma_f32 v64, v95, v78, v97
	v_fmac_f32_e32 v64, v89, v79
	v_lshlrev_b32_e32 v81, 16, v172
	v_fmac_f32_e32 v64, v94, v80
	v_fmac_f32_e32 v64, v96, v81
	v_cvt_pk_bf16_f32 v64, v64, s0
	ds_write_b16 v168, v64 offset:3808
	v_fma_f32 v64, v95, v79, v97
	v_fmac_f32_e32 v64, v89, v80
	v_lshlrev_b32_e32 v82, 16, v174
	v_fmac_f32_e32 v64, v94, v81
	v_fmac_f32_e32 v64, v96, v82
	v_cvt_pk_bf16_f32 v64, v64, s0
	s_mov_b32 s0, s17
	s_add_i32 s17, s17, 1
	s_cmp_lg_u32 s0, 7
	s_cselect_b32 s22, s17, 7
	s_sub_i32 s23, 7, s22
	s_and_b64 s[0:1], s[4:5], exec
	s_cselect_b32 s0, s22, s23
	ds_write_b16 v169, v64
	v_lshl_add_u32 v64, s0, 5, v132
	v_cmp_lt_i32_e32 vcc, 0, v64
	v_add_u32_e32 v65, 17, v64
	v_cmp_gt_i32_e64 s[0:1], s29, v65
	s_mov_b64 s[98:99], 0x1800
	s_and_b64 s[0:1], vcc, s[0:1]
	s_cmp_eq_u64 s[0:1], exec
	s_cbranch_scc0 .Lxload_slow_3
	v_add_u32_e32 v66, s16, v64
	v_mov_b32_e32 v67, 0
	v_lshlrev_b64 v[66:67], 11, v[66:67]
	v_lshl_add_u64 v[66:67], v[92:93], 0, v[66:67]
	global_load_ushort v103, v[66:67], off offset:-2048
	global_load_ushort v102, v[66:67], off
	global_load_ushort v105, v[66:67], off offset:2048
	v_lshl_add_u64 v[66:67], v[66:67], 0, s[98:99]
	global_load_ushort v104, v[66:67], off offset:-2048
	global_load_ushort v107, v[66:67], off
	global_load_ushort v106, v[66:67], off offset:2048
	v_lshl_add_u64 v[66:67], v[66:67], 0, s[98:99]
	global_load_ushort v123, v[66:67], off offset:-2048
	global_load_ushort v122, v[66:67], off
	global_load_ushort v125, v[66:67], off offset:2048
	v_lshl_add_u64 v[66:67], v[66:67], 0, s[98:99]
	global_load_ushort v124, v[66:67], off offset:-2048
	global_load_ushort v128, v[66:67], off
	global_load_ushort v127, v[66:67], off offset:2048
	v_lshl_add_u64 v[66:67], v[66:67], 0, s[98:99]
	global_load_ushort v130, v[66:67], off offset:-2048
	global_load_ushort v129, v[66:67], off
	global_load_ushort v171, v[66:67], off offset:2048
	v_lshl_add_u64 v[66:67], v[66:67], 0, s[98:99]
	global_load_ushort v170, v[66:67], off offset:-2048
	global_load_ushort v173, v[66:67], off
	global_load_ushort v172, v[66:67], off offset:2048
	v_lshl_add_u64 v[66:67], v[66:67], 0, s[98:99]
	global_load_ushort v174, v[66:67], off offset:-2048
	s_branch .LBB0_593
.Lxload_slow_3:
	v_cmp_lt_i32_e32 vcc, 0, v64
	v_cmp_ge_i32_e64 s[0:1], s29, v64
	s_and_b64 s[22:23], vcc, s[0:1]
	v_mov_b32_e32 v102, 0
	v_mov_b32_e32 v103, 0
	s_and_saveexec_b64 s[0:1], s[22:23]
	s_cbranch_execz .LBB0_557
	v_add_u32_e32 v66, s25, v64
	v_ashrrev_i32_e32 v67, 31, v66
	v_lshlrev_b64 v[66:67], 11, v[66:67]
	v_lshl_add_u64 v[66:67], v[92:93], 0, v[66:67]
	global_load_ushort v103, v[66:67], off

.LBB0_759:
	s_waitcnt vmcnt(8)
	v_lshlrev_b32_e32 v64, 16, v105
	v_lshlrev_b32_e32 v65, 16, v107
	v_fma_f32 v64, v98, v64, v100
	v_lshlrev_b32_e32 v66, 16, v122
	v_fmac_f32_e32 v64, v96, v65
	v_lshlrev_b32_e32 v67, 16, v123
	v_fmac_f32_e32 v64, v97, v66
	v_fmac_f32_e32 v64, v99, v67
	v_cvt_pk_bf16_f32 v64, v64, s0
	ds_write_b16 v173, v64
	v_fma_f32 v64, v98, v65, v100
	v_fmac_f32_e32 v64, v96, v66
	v_lshlrev_b32_e32 v68, 16, v124
	v_fmac_f32_e32 v64, v97, v67
	v_fmac_f32_e32 v64, v99, v68
	v_cvt_pk_bf16_f32 v64, v64, s0
	ds_write_b16 v173, v64 offset:272
	v_fma_f32 v64, v98, v66, v100
	v_fmac_f32_e32 v64, v96, v67
	v_lshlrev_b32_e32 v69, 16, v125
	v_fmac_f32_e32 v64, v97, v68
	v_fmac_f32_e32 v64, v99, v69
	v_cvt_pk_bf16_f32 v64, v64, s0
	ds_write_b16 v173, v64 offset:544
	v_fma_f32 v64, v98, v67, v100
	v_fmac_f32_e32 v64, v96, v68
	v_lshlrev_b32_e32 v70, 16, v126
	v_fmac_f32_e32 v64, v97, v69
	v_fmac_f32_e32 v64, v99, v70
	v_cvt_pk_bf16_f32 v64, v64, s0
	ds_write_b16 v173, v64 offset:816
	v_fma_f32 v64, v98, v68, v100
	v_fmac_f32_e32 v64, v96, v69
	v_lshlrev_b32_e32 v71, 16, v127
	v_fmac_f32_e32 v64, v97, v70
	v_fmac_f32_e32 v64, v99, v71
	v_cvt_pk_bf16_f32 v64, v64, s0
	ds_write_b16 v173, v64 offset:1088
	v_fma_f32 v64, v98, v69, v100
	v_fmac_f32_e32 v64, v96, v70
	v_lshlrev_b32_e32 v72, 16, v128
	v_fmac_f32_e32 v64, v97, v71
	v_fmac_f32_e32 v64, v99, v72
	v_cvt_pk_bf16_f32 v64, v64, s0
	ds_write_b16 v173, v64 offset:1360
	v_fma_f32 v64, v98, v70, v100
	v_fmac_f32_e32 v64, v96, v71
	v_lshlrev_b32_e32 v73, 16, v129
	v_fmac_f32_e32 v64, v97, v72
	v_fmac_f32_e32 v64, v99, v73
	v_cvt_pk_bf16_f32 v64, v64, s0
	ds_write_b16 v173, v64 offset:1632
	v_fma_f32 v64, v98, v71, v100
	v_fmac_f32_e32 v64, v96, v72
	v_lshlrev_b32_e32 v74, 16, v130
	v_fmac_f32_e32 v64, v97, v73
	v_fmac_f32_e32 v64, v99, v74
	v_cvt_pk_bf16_f32 v64, v64, s0
	ds_write_b16 v173, v64 offset:1904
	v_fma_f32 v64, v98, v72, v100
	v_fmac_f32_e32 v64, v96, v73
	v_lshlrev_b32_e32 v75, 16, v132
	v_fmac_f32_e32 v64, v97, v74
	v_fmac_f32_e32 v64, v99, v75
	v_cvt_pk_bf16_f32 v64, v64, s0
	ds_write_b16 v173, v64 offset:2176
	v_fma_f32 v64, v98, v73, v100
	v_fmac_f32_e32 v64, v96, v74
	v_lshlrev_b32_e32 v76, 16, v133
	v_fmac_f32_e32 v64, v97, v75
	v_fmac_f32_e32 v64, v99, v76
	v_cvt_pk_bf16_f32 v64, v64, s0
	ds_write_b16 v173, v64 offset:2448
	v_fma_f32 v64, v98, v74, v100
	v_fmac_f32_e32 v64, v96, v75
	v_lshlrev_b32_e32 v77, 16, v134
	v_fmac_f32_e32 v64, v97, v76
	v_fmac_f32_e32 v64, v99, v77
	v_cvt_pk_bf16_f32 v64, v64, s0
	ds_write_b16 v173, v64 offset:2720
	v_fma_f32 v64, v98, v75, v100
	v_fmac_f32_e32 v64, v96, v76
	v_lshlrev_b32_e32 v78, 16, v166
	v_fmac_f32_e32 v64, v97, v77
	v_fmac_f32_e32 v64, v99, v78
	v_cvt_pk_bf16_f32 v64, v64, s0
	ds_write_b16 v173, v64 offset:2992
	v_fma_f32 v64, v98, v76, v100
	v_fmac_f32_e32 v64, v96, v77
	v_lshlrev_b32_e32 v79, 16, v175
	v_fmac_f32_e32 v64, v97, v78
	v_fmac_f32_e32 v64, v99, v79
	v_cvt_pk_bf16_f32 v64, v64, s0
	ds_write_b16 v173, v64 offset:3264
	v_fma_f32 v64, v98, v77, v100
	v_fmac_f32_e32 v64, v96, v78
	v_lshlrev_b32_e32 v80, 16, v176
	v_fmac_f32_e32 v64, v97, v79
	v_fmac_f32_e32 v64, v99, v80
	v_cvt_pk_bf16_f32 v64, v64, s0
	ds_write_b16 v173, v64 offset:3536
	v_fma_f32 v64, v98, v78, v100
	v_fmac_f32_e32 v64, v96, v79
	v_lshlrev_b32_e32 v81, 16, v177
	v_fmac_f32_e32 v64, v97, v80
	v_fmac_f32_e32 v64, v99, v81
	v_cvt_pk_bf16_f32 v64, v64, s0
	ds_write_b16 v173, v64 offset:3808
	v_fma_f32 v64, v98, v79, v100
	v_fmac_f32_e32 v64, v96, v80
	v_lshlrev_b32_e32 v82, 16, v178
	v_fmac_f32_e32 v64, v97, v81
	v_fmac_f32_e32 v64, v99, v82
	s_add_i32 s27, s5, 1
	v_cvt_pk_bf16_f32 v64, v64, s0
	s_lshl_b32 s0, s27, 5
	s_cmp_lg_u32 s5, 7
	s_cselect_b32 s0, s0, 0xe0
	ds_write_b16 v174, v64
	v_add_u32_e32 v64, s0, v106
	v_cmp_lt_i32_e32 vcc, 0, v64
	v_add_u32_e32 v65, 17, v64
	v_cmp_gt_i32_e64 s[0:1], s19, v65
	s_mov_b64 s[98:99], 0x1800
	s_and_b64 s[0:1], vcc, s[0:1]
	s_cmp_eq_u64 s[0:1], exec
	s_cbranch_scc0 .Lxload_slow_2
	v_add_u32_e32 v66, s20, v64
	v_mov_b32_e32 v67, 0
	v_lshlrev_b64 v[66:67], 11, v[66:67]
	v_lshl_add_u64 v[66:67], v[92:93], 0, v[66:67]
	global_load_ushort v105, v[66:67], off offset:-2048
	global_load_ushort v107, v[66:67], off
	global_load_ushort v122, v[66:67], off offset:2048
	v_lshl_add_u64 v[66:67], v[66:67], 0, s[98:99]
	global_load_ushort v123, v[66:67], off offset:-2048
	global_load_ushort v124, v[66:67], off
	global_load_ushort v125, v[66:67], off offset:2048
	v_lshl_add_u64 v[66:67], v[66:67], 0, s[98:99]
	global_load_ushort v126, v[66:67], off offset:-2048
	global_load_ushort v127, v[66:67], off
	global_load_ushort v128, v[66:67], off offset:2048
	v_lshl_add_u64 v[66:67], v[66:67], 0, s[98:99]
	global_load_ushort v129, v[66:67], off offset:-2048
	global_load_ushort v130, v[66:67], off
	global_load_ushort v132, v[66:67], off offset:2048
	v_lshl_add_u64 v[66:67], v[66:67], 0, s[98:99]
	global_load_ushort v133, v[66:67], off offset:-2048
	global_load_ushort v134, v[66:67], off
	global_load_ushort v166, v[66:67], off offset:2048
	v_lshl_add_u64 v[66:67], v[66:67], 0, s[98:99]
	global_load_ushort v175, v[66:67], off offset:-2048
	global_load_ushort v176, v[66:67], off
	global_load_ushort v177, v[66:67], off offset:2048
	v_lshl_add_u64 v[66:67], v[66:67], 0, s[98:99]
	global_load_ushort v178, v[66:67], off offset:-2048
	s_branch .LBB0_797
.Lxload_slow_2:
	v_cmp_lt_i32_e32 vcc, 0, v64
	v_cmp_ge_i32_e64 s[0:1], s19, v64
	s_and_b64 s[28:29], vcc, s[0:1]
	v_mov_b32_e32 v107, 0
	v_mov_b32_e32 v105, 0
	s_and_saveexec_b64 s[0:1], s[28:29]
	s_cbranch_execz .LBB0_761
	v_add_u32_e32 v66, s21, v64
	v_ashrrev_i32_e32 v67, 31, v66
	v_lshlrev_b64 v[66:67], 11, v[66:67]
	v_lshl_add_u64 v[66:67], v[92:93], 0, v[66:67]
	global_load_ushort v105, v[66:67], off

.LBB0_848:
	v_lshlrev_b32_e32 v64, 16, v107
	v_lshlrev_b32_e32 v65, 16, v122
	v_fma_f32 v64, v98, v64, v102
	v_lshlrev_b32_e32 v66, 16, v123
	v_fmac_f32_e32 v64, v99, v65
	v_lshlrev_b32_e32 v67, 16, v124
	v_fmac_f32_e32 v64, v100, v66
	v_fmac_f32_e32 v64, v101, v67
	v_cvt_pk_bf16_f32 v64, v64, s0
	ds_write_b16 v174, v64
	v_fma_f32 v64, v98, v65, v102
	v_fmac_f32_e32 v64, v99, v66
	v_lshlrev_b32_e32 v68, 16, v125
	v_fmac_f32_e32 v64, v100, v67
	v_fmac_f32_e32 v64, v101, v68
	v_cvt_pk_bf16_f32 v64, v64, s0
	ds_write_b16 v174, v64 offset:272
	v_fma_f32 v64, v98, v66, v102
	v_fmac_f32_e32 v64, v99, v67
	v_lshlrev_b32_e32 v69, 16, v126
	v_fmac_f32_e32 v64, v100, v68
	v_fmac_f32_e32 v64, v101, v69
	v_cvt_pk_bf16_f32 v64, v64, s0
	ds_write_b16 v174, v64 offset:544
	v_fma_f32 v64, v98, v67, v102
	v_fmac_f32_e32 v64, v99, v68
	v_lshlrev_b32_e32 v70, 16, v127
	v_fmac_f32_e32 v64, v100, v69
	v_fmac_f32_e32 v64, v101, v70
	v_cvt_pk_bf16_f32 v64, v64, s0
	ds_write_b16 v174, v64 offset:816
	v_fma_f32 v64, v98, v68, v102
	v_fmac_f32_e32 v64, v99, v69
	v_lshlrev_b32_e32 v71, 16, v128
	v_fmac_f32_e32 v64, v100, v70
	v_fmac_f32_e32 v64, v101, v71
	v_cvt_pk_bf16_f32 v64, v64, s0
	ds_write_b16 v174, v64 offset:1088
	v_fma_f32 v64, v98, v69, v102
	v_fmac_f32_e32 v64, v99, v70
	v_lshlrev_b32_e32 v72, 16, v129
	v_fmac_f32_e32 v64, v100, v71
	v_fmac_f32_e32 v64, v101, v72
	v_cvt_pk_bf16_f32 v64, v64, s0
	ds_write_b16 v174, v64 offset:1360
	v_fma_f32 v64, v98, v70, v102
	v_fmac_f32_e32 v64, v99, v71
	v_lshlrev_b32_e32 v73, 16, v130
	v_fmac_f32_e32 v64, v100, v72
	v_fmac_f32_e32 v64, v101, v73
	v_cvt_pk_bf16_f32 v64, v64, s0
	ds_write_b16 v174, v64 offset:1632
	v_fma_f32 v64, v98, v71, v102
	v_fmac_f32_e32 v64, v99, v72
	v_lshlrev_b32_e32 v74, 16, v131
	v_fmac_f32_e32 v64, v100, v73
	v_fmac_f32_e32 v64, v101, v74
	v_cvt_pk_bf16_f32 v64, v64, s0
	ds_write_b16 v174, v64 offset:1904
	v_fma_f32 v64, v98, v72, v102
	v_fmac_f32_e32 v64, v99, v73
	v_lshlrev_b32_e32 v75, 16, v133
	v_fmac_f32_e32 v64, v100, v74
	v_fmac_f32_e32 v64, v101, v75
	v_cvt_pk_bf16_f32 v64, v64, s0
	ds_write_b16 v174, v64 offset:2176
	v_fma_f32 v64, v98, v73, v102
	v_fmac_f32_e32 v64, v99, v74
	v_lshlrev_b32_e32 v76, 16, v134
	v_fmac_f32_e32 v64, v100, v75
	v_fmac_f32_e32 v64, v101, v76
	v_cvt_pk_bf16_f32 v64, v64, s0
	ds_write_b16 v174, v64 offset:2448
	v_fma_f32 v64, v98, v74, v102
	v_fmac_f32_e32 v64, v99, v75
	v_lshlrev_b32_e32 v77, 16, v135
	v_fmac_f32_e32 v64, v100, v76
	v_fmac_f32_e32 v64, v101, v77
	v_cvt_pk_bf16_f32 v64, v64, s0
	ds_write_b16 v174, v64 offset:2720
	v_fma_f32 v64, v98, v75, v102
	v_fmac_f32_e32 v64, v99, v76
	v_lshlrev_b32_e32 v78, 16, v175
	v_fmac_f32_e32 v64, v100, v77
	v_fmac_f32_e32 v64, v101, v78
	v_cvt_pk_bf16_f32 v64, v64, s0
	ds_write_b16 v174, v64 offset:2992
	v_fma_f32 v64, v98, v76, v102
	v_fmac_f32_e32 v64, v99, v77
	v_lshlrev_b32_e32 v79, 16, v177
	v_fmac_f32_e32 v64, v100, v78
	v_fmac_f32_e32 v64, v101, v79
	v_cvt_pk_bf16_f32 v64, v64, s0
	ds_write_b16 v174, v64 offset:3264
	v_fma_f32 v64, v98, v77, v102
	v_fmac_f32_e32 v64, v99, v78
	v_lshlrev_b32_e32 v80, 16, v178
	v_fmac_f32_e32 v64, v100, v79
	v_fmac_f32_e32 v64, v101, v80
	v_cvt_pk_bf16_f32 v64, v64, s0
	ds_write_b16 v174, v64 offset:3536
	v_fma_f32 v64, v98, v78, v102
	v_fmac_f32_e32 v64, v99, v79
	v_lshlrev_b32_e32 v81, 16, v179
	v_fmac_f32_e32 v64, v100, v80
	v_fmac_f32_e32 v64, v101, v81
	v_cvt_pk_bf16_f32 v64, v64, s0
	ds_write_b16 v174, v64 offset:3808
	v_fma_f32 v64, v98, v79, v102
	v_fmac_f32_e32 v64, v99, v80
	v_lshlrev_b32_e32 v82, 16, v180
	v_fmac_f32_e32 v64, v100, v81
	v_fmac_f32_e32 v64, v101, v82
	s_lshl_b32 s8, s5, 5
	v_cvt_pk_bf16_f32 v64, v64, s0
	s_sub_i32 s0, 0xc0, s8
	s_cmp_lg_u32 s5, 7
	s_cselect_b32 s0, s0, 0
	ds_write_b16 v176, v64
	v_add_u32_e32 v64, s0, v137
	v_cmp_lt_i32_e32 vcc, 0, v64
	v_add_u32_e32 v65, 17, v64
	v_cmp_gt_i32_e64 s[0:1], s19, v65
	s_mov_b64 s[98:99], 0x1800
	s_and_b64 s[0:1], vcc, s[0:1]
	s_cmp_eq_u64 s[0:1], exec
	s_cbranch_scc0 .Lxload_slow_1
	v_add_u32_e32 v66, s20, v64
	v_mov_b32_e32 v67, 0
	v_lshlrev_b64 v[66:67], 11, v[66:67]
	v_lshl_add_u64 v[66:67], v[92:93], 0, v[66:67]
	global_load_ushort v107, v[66:67], off offset:-2048
	global_load_ushort v122, v[66:67], off
	global_load_ushort v123, v[66:67], off offset:2048
	v_lshl_add_u64 v[66:67], v[66:67], 0, s[98:99]
	global_load_ushort v124, v[66:67], off offset:-2048
	global_load_ushort v125, v[66:67], off
	global_load_ushort v126, v[66:67], off offset:2048
	v_lshl_add_u64 v[66:67], v[66:67], 0, s[98:99]
	global_load_ushort v127, v[66:67], off offset:-2048
	global_load_ushort v128, v[66:67], off
	global_load_ushort v129, v[66:67], off offset:2048
	v_lshl_add_u64 v[66:67], v[66:67], 0, s[98:99]
	global_load_ushort v130, v[66:67], off offset:-2048
	global_load_ushort v131, v[66:67], off
	global_load_ushort v133, v[66:67], off offset:2048
	v_lshl_add_u64 v[66:67], v[66:67], 0, s[98:99]
	global_load_ushort v134, v[66:67], off offset:-2048
	global_load_ushort v135, v[66:67], off
	global_load_ushort v175, v[66:67], off offset:2048
	v_lshl_add_u64 v[66:67], v[66:67], 0, s[98:99]
	global_load_ushort v177, v[66:67], off offset:-2048
	global_load_ushort v178, v[66:67], off
	global_load_ushort v179, v[66:67], off offset:2048
	v_lshl_add_u64 v[66:67], v[66:67], 0, s[98:99]
	global_load_ushort v180, v[66:67], off offset:-2048
	s_branch .LBB0_886
.Lxload_slow_1:
	v_cmp_lt_i32_e32 vcc, 0, v64
	v_cmp_ge_i32_e64 s[0:1], s19, v64
	s_and_b64 s[10:11], vcc, s[0:1]
	v_mov_b32_e32 v122, 0
	v_mov_b32_e32 v107, 0
	s_and_saveexec_b64 s[0:1], s[10:11]
	s_cbranch_execz .LBB0_850
	v_add_u32_e32 v66, s21, v64
	v_ashrrev_i32_e32 v67, 31, v66
	v_lshlrev_b64 v[66:67], 11, v[66:67]
	v_lshl_add_u64 v[66:67], v[92:93], 0, v[66:67]
	global_load_ushort v107, v[66:67], off

.LBB0_892:
	s_lshl_b32 s2, s22, 12
	s_and_b32 s58, s5, 7
	s_addk_i32 s2, 0x1000
	s_lshl_b32 s3, s22, 8
	s_and_b64 s[0:1], s[0:1], exec
	s_cselect_b32 s0, s2, s3
	s_lshl_b32 s1, s4, 7
	s_add_i32 s0, s0, s1
	s_add_u32 s4, s64, s20
	v_lshl_or_b32 v0, v127, 5, v128
	s_addc_u32 s5, s60, s21
	s_ashr_i32 s23, s22, 31
	v_add_u32_e32 v126, s0, v0
	s_lshl_b64 s[0:1], s[22:23], 3
	s_or_b32 s70, s0, s58
	s_mul_hi_u32 s3, s55, s70
	s_mul_i32 s6, s55, s1
	s_mul_i32 s2, s55, s70
	s_add_i32 s3, s3, s6
	s_lshl_b64 s[2:3], s[2:3], 7
	s_add_u32 s90, s4, s2
	s_addc_u32 s91, s5, s3
	s_add_u32 s2, s64, s24
	s_addc_u32 s3, s60, s25
	s_lshl_b32 s71, s55, 6
	s_mul_i32 s69, s71, s22
	s_mul_hi_i32 s68, s71, s22
	s_add_u32 s30, s2, s69
	s_addc_u32 s31, s3, s68
	v_readlane_b32 s2, v215, 54
	v_readlane_b32 s3, v215, 55
	v_mov_b32_e32 v130, v111
	s_lshl_b32 s28, s58, 7
	v_mov_b64_e32 v[0:1], s[2:3]
	v_mad_i64_i32 v[0:1], s[2:3], v126, s83, v[0:1]
	s_mov_b32 s29, s87
	v_lshl_add_u64 v[2:3], v[0:1], 0, s[28:29]
	v_bfe_u32 v53, v130, 5, 1
	v_lshlrev_b32_e32 v128, 4, v53
	v_mov_b32_e32 v129, v109
	s_lshl_b32 s86, s58, 6
	v_lshl_add_u64 v[2:3], v[2:3], 0, v[128:129]
	v_lshl_add_u64 v[0:1], v[0:1], 0, s[86:87]
	global_load_dwordx4 v[20:23], v[2:3], off
	global_load_dwordx4 v[16:19], v[2:3], off offset:32
	global_load_dwordx4 v[12:15], v[2:3], off offset:64
	global_load_dwordx4 v[8:11], v[2:3], off offset:96
	v_lshl_add_u64 v[0:1], v[0:1], 0, v[128:129]
	global_load_dwordx4 v[4:7], v[0:1], off offset:1024
	s_nop 0
	global_load_dwordx4 v[0:3], v[0:1], off offset:1056
	v_mul_hi_i32 v24, v130, s75
	v_lshrrev_b32_e32 v25, 31, v24
	v_ashrrev_i32_e32 v24, 1, v24
	v_add_u32_e32 v36, v24, v25
	v_mul_lo_u32 v24, v36, 12
	v_sub_u32_e32 v55, v130, v24
	v_ashrrev_i32_e32 v37, 31, v36
	v_cmp_gt_i32_e32 vcc, 8, v55
	v_cmp_lt_i32_e64 s[6:7], 7, v55
	v_lshlrev_b32_e32 v34, 3, v55
	v_lshlrev_b64 v[38:39], 6, v[36:37]
	s_and_saveexec_b64 s[2:3], s[6:7]
	s_xor_b64 s[2:3], exec, s[2:3]
	v_lshl_add_u64 v[24:25], s[30:31], 0, v[38:39]
	v_mov_b32_e32 v35, v109
	s_movk_i32 s4, 0xff80
	v_lshl_add_u64 v[24:25], v[34:35], 1, v[24:25]
	s_mov_b32 s5, -1
	v_lshl_add_u64 v[24:25], v[24:25], 0, s[4:5]
	s_or_saveexec_b64 s[2:3], s[2:3]
	v_lshlrev_b64 v[32:33], 7, v[36:37]
	v_ashrrev_i32_e32 v37, 31, v34
	s_xor_b64 exec, exec, s[2:3]
	v_lshl_add_u64 v[24:25], s[90:91], 0, v[32:33]
	v_mov_b32_e32 v35, v37
	v_lshl_add_u64 v[24:25], v[34:35], 1, v[24:25]
	s_or_b64 exec, exec, s[2:3]
	global_load_dwordx4 v[24:27], v[24:25], off
	v_add_u32_e32 v52, 0x100, v130
	v_mul_hi_i32 v28, v52, s75
	v_lshrrev_b32_e32 v29, 31, v28
	v_ashrrev_i32_e32 v28, 1, v28
	v_add_u32_e32 v42, v28, v29
	v_mul_lo_u32 v28, v42, 12
	v_sub_u32_e32 v35, v52, v28
	v_ashrrev_i32_e32 v43, 31, v42
	v_cmp_gt_i32_e64 s[2:3], 8, v35
	v_cmp_lt_i32_e64 s[8:9], 7, v35
	v_lshlrev_b32_e32 v44, 3, v35
	v_lshlrev_b64 v[46:47], 6, v[42:43]
	s_and_saveexec_b64 s[4:5], s[8:9]
	s_xor_b64 s[4:5], exec, s[4:5]
	v_lshl_add_u64 v[28:29], s[30:31], 0, v[46:47]
	v_mov_b32_e32 v45, v109
	s_movk_i32 s10, 0xff80
	v_lshl_add_u64 v[28:29], v[44:45], 1, v[28:29]
	s_mov_b32 s11, -1
	v_lshl_add_u64 v[28:29], v[28:29], 0, s[10:11]
	s_or_saveexec_b64 s[4:5], s[4:5]
	v_lshlrev_b64 v[40:41], 7, v[42:43]
	v_ashrrev_i32_e32 v43, 31, v44
	s_xor_b64 exec, exec, s[4:5]
	v_lshl_add_u64 v[28:29], s[90:91], 0, v[40:41]
	v_mov_b32_e32 v45, v43
	v_lshl_add_u64 v[28:29], v[44:45], 1, v[28:29]
	s_or_b64 exec, exec, s[4:5]
	global_load_dwordx4 v[28:31], v[28:29], off
	v_add_u32_e32 v45, 0x200, v130
	v_mul_hi_i32 v48, v45, s75
	v_lshrrev_b32_e32 v49, 31, v48
	v_ashrrev_i32_e32 v48, 1, v48
	v_add_u32_e32 v60, v48, v49
	v_mul_lo_u32 v48, v60, 12
	v_sub_u32_e32 v45, v45, v48
	v_ashrrev_i32_e32 v61, 31, v60
	v_cmp_gt_i32_e64 s[4:5], 8, v45
	v_cmp_lt_i32_e64 s[10:11], 7, v45
	v_lshlrev_b32_e32 v108, 3, v45
	v_lshlrev_b64 v[48:49], 6, v[60:61]
	s_and_saveexec_b64 s[72:73], s[10:11]
	s_xor_b64 s[92:93], exec, s[72:73]
	v_lshlrev_b64 v[50:51], 6, v[60:61]
	v_lshl_add_u64 v[50:51], s[30:31], 0, v[50:51]
	s_movk_i32 s36, 0xff80
	v_lshl_add_u64 v[50:51], v[108:109], 1, v[50:51]
	s_mov_b32 s37, -1
	v_lshl_add_u64 v[64:65], v[50:51], 0, s[36:37]
	s_or_saveexec_b64 s[92:93], s[92:93]
	v_ashrrev_i32_e32 v63, 31, v108
	v_lshlrev_b64 v[50:51], 7, v[60:61]
	s_xor_b64 exec, exec, s[92:93]
	v_lshlrev_b64 v[56:57], 7, v[60:61]
	v_lshl_add_u64 v[56:57], s[90:91], 0, v[56:57]
	v_mov_b32_e32 v62, v108
	v_lshl_add_u64 v[64:65], v[62:63], 1, v[56:57]
	s_or_b64 exec, exec, s[92:93]
	s_add_u32 s29, s64, s26
	s_mul_i32 s72, s1, s71
	s_mul_hi_u32 s73, s70, s71
	s_addc_u32 s74, s60, s27
	s_add_i32 s73, s73, s72
	s_mul_i32 s72, s70, s71
	s_lshl_b64 s[70:71], s[72:73], 1
	s_add_u32 s70, s29, s70
	v_ashrrev_i32_e32 v54, 3, v130
	v_lshlrev_b32_e32 v58, 4, v130
	v_ashrrev_i32_e32 v52, 3, v52
	s_addc_u32 s71, s74, s71
	v_mad_i64_i32 v[56:57], s[72:73], v54, s55, 0
	v_and_b32_e32 v124, 0x70, v58
	v_mad_i64_i32 v[58:59], s[72:73], v52, s55, 0
	v_lshl_add_u64 v[56:57], v[56:57], 1, s[70:71]
	v_mov_b32_e32 v125, v109
	v_lshl_add_u64 v[58:59], v[58:59], 1, s[70:71]
	s_movk_i32 s29, 0xd0
	v_lshl_add_u64 v[56:57], v[56:57], 0, v[124:125]
	v_lshl_add_u64 v[58:59], v[58:59], 0, v[124:125]
	v_mul_lo_u32 v123, v36, s29
	v_lshlrev_b32_e32 v125, 4, v55
	v_add_u32_e32 v36, v123, v125
	v_mul_lo_u32 v129, v42, s29
	v_lshlrev_b32_e32 v166, 4, v35
	s_waitcnt vmcnt(1)
	ds_write_b128 v36, v[24:27]
	v_add_u32_e32 v24, v129, v166
	s_waitcnt vmcnt(0)
	ds_write_b128 v24, v[28:31]
	global_load_dwordx4 v[24:27], v[64:65], off
	global_load_dwordx4 v[66:69], v[56:57], off
	global_load_dwordx4 v[70:73], v[58:59], off
	v_mul_lo_u32 v167, v60, s29
	v_lshlrev_b32_e32 v168, 4, v45
	s_movk_i32 s29, 0x88
	s_add_u32 s90, s90, 0x2000
	v_add_u32_e32 v28, v167, v168
	v_mul_lo_u32 v169, v54, s29
	s_addc_u32 s91, s91, 0
	v_mul_lo_u32 v170, v52, s29
	s_add_u32 s30, s30, 0x1000
	s_movk_i32 s74, 0xd0
	s_addc_u32 s31, s31, 0
	s_waitcnt vmcnt(2)
	ds_write_b128 v28, v[24:27]
	v_add3_u32 v24, v169, v124, s63
	s_waitcnt vmcnt(1)
	ds_write2_b64 v24, v[66:67], v[68:69] offset1:1
	v_add3_u32 v24, v170, v124, s63
	s_waitcnt vmcnt(0)
	ds_write2_b64 v24, v[70:71], v[72:73] offset1:1
	s_and_saveexec_b64 s[70:71], s[6:7]
	s_xor_b64 s[6:7], exec, s[70:71]
	s_mov_b32 s75, 0x2aaaaaab
	v_lshl_add_u64 v[24:25], s[30:31], 0, v[38:39]
	v_mov_b32_e32 v35, v109
	s_movk_i32 s36, 0xff80
	v_lshl_add_u64 v[24:25], v[34:35], 1, v[24:25]
	s_mov_b32 s37, -1
	v_lshl_add_u64 v[24:25], v[24:25], 0, s[36:37]
	s_andn2_saveexec_b64 s[6:7], s[6:7]
	v_lshl_add_u64 v[24:25], s[90:91], 0, v[32:33]
	v_mov_b32_e32 v35, v37
	v_lshl_add_u64 v[24:25], v[34:35], 1, v[24:25]
	s_or_b64 exec, exec, s[6:7]
	global_load_dwordx4 v[64:67], v[24:25], off
	s_and_saveexec_b64 s[6:7], s[8:9]
	s_xor_b64 s[6:7], exec, s[6:7]
	v_lshl_add_u64 v[24:25], s[30:31], 0, v[46:47]
	v_mov_b32_e32 v45, v109
	s_movk_i32 s8, 0xff80
	v_lshl_add_u64 v[24:25], v[44:45], 1, v[24:25]
	s_mov_b32 s9, -1
	v_lshl_add_u64 v[24:25], v[24:25], 0, s[8:9]
	s_andn2_saveexec_b64 s[6:7], s[6:7]
	v_lshl_add_u64 v[24:25], s[90:91], 0, v[40:41]
	v_mov_b32_e32 v45, v43
	v_lshl_add_u64 v[24:25], v[44:45], 1, v[24:25]
	s_or_b64 exec, exec, s[6:7]
	global_load_dwordx4 v[76:79], v[24:25], off
	s_and_saveexec_b64 s[6:7], s[10:11]
	s_xor_b64 s[6:7], exec, s[6:7]
	v_lshlrev_b64 v[48:49], 6, v[60:61]
	v_lshl_add_u64 v[24:25], s[30:31], 0, v[48:49]
	s_movk_i32 s8, 0xff80
	v_lshl_add_u64 v[24:25], v[108:109], 1, v[24:25]
	s_mov_b32 s9, -1
	v_lshl_add_u64 v[26:27], v[24:25], 0, s[8:9]
	v_lshlrev_b64 v[50:51], 7, v[60:61]
	s_or_saveexec_b64 s[6:7], s[6:7]
	v_mov_b64_e32 v[24:25], v[108:109]
	s_xor_b64 exec, exec, s[6:7]
	v_lshl_add_u64 v[24:25], s[90:91], 0, v[50:51]
	v_mov_b32_e32 v62, v108
	v_lshl_add_u64 v[26:27], v[62:63], 1, v[24:25]
	v_mov_b64_e32 v[24:25], v[62:63]
	s_or_b64 exec, exec, s[6:7]
	global_load_dwordx4 v[96:99], v[26:27], off
	global_load_dwordx4 v[100:103], v[56:57], off offset:128
	global_load_dwordx4 v[104:107], v[58:59], off offset:128
	s_lshr_b32 s7, s55, 6
	v_lshlrev_b32_e32 v28, 16, v20
	v_and_b32_e32 v29, 0xffff0000, v20
	s_mov_b32 s6, 0x3e16c740
	v_lshlrev_b32_e32 v20, 16, v21
	v_and_b32_e32 v21, 0xffff0000, v21
	v_pk_mul_f32 v[20:21], v[20:21], s[6:7] op_sel_hi:[1,0]
	s_lshl_b64 s[8:9], s[22:23], 10
	v_cvt_pk_bf16_f32 v69, v20, v21
	v_lshlrev_b32_e32 v20, 16, v22
	v_and_b32_e32 v21, 0xffff0000, v22
	v_pk_mul_f32 v[20:21], v[20:21], s[6:7] op_sel_hi:[1,0]
	v_ashrrev_i32_e32 v55, 31, v54
	v_cvt_pk_bf16_f32 v70, v20, v21
	v_lshlrev_b32_e32 v20, 16, v23
	v_and_b32_e32 v21, 0xffff0000, v23
	v_pk_mul_f32 v[20:21], v[20:21], s[6:7] op_sel_hi:[1,0]
	s_or_b32 s8, s8, s28
	v_cvt_pk_bf16_f32 v71, v20, v21
	v_lshlrev_b32_e32 v20, 16, v16
	v_and_b32_e32 v21, 0xffff0000, v16
	v_lshlrev_b32_e32 v16, 16, v17
	v_and_b32_e32 v17, 0xffff0000, v17
	v_pk_mul_f32 v[16:17], v[16:17], s[6:7] op_sel_hi:[1,0]
	v_readlane_b32 s36, v215, 6
	v_cvt_pk_bf16_f32 v73, v16, v17
	v_lshlrev_b32_e32 v16, 16, v18
	v_and_b32_e32 v17, 0xffff0000, v18
	v_pk_mul_f32 v[16:17], v[16:17], s[6:7] op_sel_hi:[1,0]
	v_lshlrev_b32_e32 v122, 3, v53
	v_cvt_pk_bf16_f32 v74, v16, v17
	v_lshlrev_b32_e32 v16, 16, v19
	v_and_b32_e32 v17, 0xffff0000, v19
	v_pk_mul_f32 v[16:17], v[16:17], s[6:7] op_sel_hi:[1,0]
	v_ashrrev_i32_e32 v53, 31, v52
	v_cvt_pk_bf16_f32 v75, v16, v17
	v_lshlrev_b32_e32 v16, 16, v12
	v_and_b32_e32 v17, 0xffff0000, v12
	v_lshlrev_b32_e32 v12, 16, v13
	v_and_b32_e32 v13, 0xffff0000, v13
	v_pk_mul_f32 v[12:13], v[12:13], s[6:7] op_sel_hi:[1,0]
	v_readlane_b32 s50, v215, 20
	v_cvt_pk_bf16_f32 v85, v12, v13
	v_lshlrev_b32_e32 v12, 16, v14
	v_and_b32_e32 v13, 0xffff0000, v14
	v_pk_mul_f32 v[12:13], v[12:13], s[6:7] op_sel_hi:[1,0]
	v_readlane_b32 s51, v215, 21
	v_cvt_pk_bf16_f32 v86, v12, v13
	v_lshlrev_b32_e32 v12, 16, v15
	v_and_b32_e32 v13, 0xffff0000, v15
	v_pk_mul_f32 v[12:13], v[12:13], s[6:7] op_sel_hi:[1,0]
	v_pk_mul_f32 v[28:29], v[28:29], s[6:7] op_sel_hi:[1,0]
	v_cvt_pk_bf16_f32 v87, v12, v13
	v_lshlrev_b32_e32 v12, 16, v8
	v_and_b32_e32 v13, 0xffff0000, v8
	v_lshlrev_b32_e32 v8, 16, v9
	v_and_b32_e32 v9, 0xffff0000, v9
	v_pk_mul_f32 v[8:9], v[8:9], s[6:7] op_sel_hi:[1,0]
	v_pk_mul_f32 v[20:21], v[20:21], s[6:7] op_sel_hi:[1,0]
	v_cvt_pk_bf16_f32 v81, v8, v9
	v_lshlrev_b32_e32 v8, 16, v10
	v_and_b32_e32 v9, 0xffff0000, v10
	v_pk_mul_f32 v[8:9], v[8:9], s[6:7] op_sel_hi:[1,0]
	v_pk_mul_f32 v[16:17], v[16:17], s[6:7] op_sel_hi:[1,0]
	v_cvt_pk_bf16_f32 v82, v8, v9
	v_lshlrev_b32_e32 v8, 16, v11
	v_and_b32_e32 v9, 0xffff0000, v11
	v_pk_mul_f32 v[8:9], v[8:9], s[6:7] op_sel_hi:[1,0]
	v_pk_mul_f32 v[12:13], v[12:13], s[6:7] op_sel_hi:[1,0]
	v_cvt_pk_bf16_f32 v83, v8, v9
	v_lshlrev_b32_e32 v8, 16, v4
	v_and_b32_e32 v9, 0xffff0000, v4
	v_lshlrev_b32_e32 v4, 16, v5
	v_and_b32_e32 v5, 0xffff0000, v5
	v_pk_mul_f32 v[4:5], v[4:5], s[6:7] op_sel_hi:[1,0]
	v_pk_mul_f32 v[8:9], v[8:9], s[6:7] op_sel_hi:[1,0]
	v_cvt_pk_bf16_f32 v93, v4, v5
	v_lshlrev_b32_e32 v4, 16, v6
	v_and_b32_e32 v5, 0xffff0000, v6
	v_pk_mul_f32 v[4:5], v[4:5], s[6:7] op_sel_hi:[1,0]
	v_mov_b32_e32 v35, v109
	v_cvt_pk_bf16_f32 v94, v4, v5
	v_lshlrev_b32_e32 v4, 16, v7
	v_and_b32_e32 v5, 0xffff0000, v7
	v_pk_mul_f32 v[4:5], v[4:5], s[6:7] op_sel_hi:[1,0]
	v_mov_b32_e32 v45, v109
	v_cvt_pk_bf16_f32 v95, v4, v5
	v_lshlrev_b32_e32 v4, 16, v0
	v_and_b32_e32 v5, 0xffff0000, v0
	v_lshlrev_b32_e32 v0, 16, v1
	v_and_b32_e32 v1, 0xffff0000, v1
	v_pk_mul_f32 v[0:1], v[0:1], s[6:7] op_sel_hi:[1,0]
	v_pk_mul_f32 v[4:5], v[4:5], s[6:7] op_sel_hi:[1,0]
	v_cvt_pk_bf16_f32 v89, v0, v1
	v_lshlrev_b32_e32 v0, 16, v2
	v_and_b32_e32 v1, 0xffff0000, v2
	v_pk_mul_f32 v[0:1], v[0:1], s[6:7] op_sel_hi:[1,0]
	v_cvt_pk_bf16_f32 v88, v4, v5
	v_cvt_pk_bf16_f32 v90, v0, v1
	v_lshlrev_b32_e32 v0, 16, v3
	v_and_b32_e32 v1, 0xffff0000, v3
	v_pk_mul_f32 v[0:1], v[0:1], s[6:7] op_sel_hi:[1,0]
	v_mov_b64_e32 v[2:3], s[26:27]
	v_cvt_pk_bf16_f32 v91, v0, v1
	v_and_b32_e32 v0, 31, v130
	v_mul_u32_u24_e32 v176, 0xd0, v0
	v_mul_u32_u24_e32 v175, 0x88, v0
	v_lshl_add_u64 v[0:1], v[54:55], 1, s[8:9]
	v_mad_u64_u32 v[4:5], s[10:11], v0, s55, v[2:3]
	v_and_b32_e32 v0, 7, v130
	v_mad_i32_i24 v5, v1, s55, v5
	v_lshlrev_b32_e32 v0, 4, v0
	v_mov_b32_e32 v1, v109
	v_lshl_add_u64 v[4:5], v[4:5], 0, v[0:1]
	v_lshl_add_u64 v[130:131], s[50:51], 0, v[4:5]
	v_lshl_add_u64 v[4:5], v[52:53], 1, s[8:9]
	s_add_i32 s7, s7, -2
	v_mad_u64_u32 v[2:3], s[8:9], v4, s55, v[2:3]
	s_add_u32 s8, s24, s69
	v_mad_i32_i24 v3, v5, s55, v3
	s_addc_u32 s9, s25, s68
	v_lshl_add_u64 v[0:1], v[2:3], 0, v[0:1]
	s_add_u32 s0, s0, s58
	v_lshl_add_u64 v[132:133], s[50:51], 0, v[0:1]
	v_lshl_add_u64 v[0:1], s[8:9], 0, v[38:39]
	v_readlane_b32 s10, v215, 4
	s_addc_u32 s1, s1, 0
	v_lshl_add_u64 v[0:1], v[34:35], 1, v[0:1]
	v_readlane_b32 s11, v215, 5
	s_mul_i32 s1, s1, s55
	s_mul_hi_u32 s6, s0, s55
	v_lshl_add_u64 v[134:135], s[10:11], 0, v[0:1]
	v_lshl_add_u64 v[0:1], s[8:9], 0, v[46:47]
	s_add_i32 s1, s6, s1
	s_mul_i32 s0, s0, s55
	v_lshl_add_u64 v[0:1], v[44:45], 1, v[0:1]
	s_lshl_b64 s[0:1], s[0:1], 7
	v_lshl_add_u64 v[136:137], s[10:11], 0, v[0:1]
	v_lshl_add_u64 v[0:1], s[8:9], 0, v[48:49]
	s_add_u32 s0, s20, s0
	v_lshl_add_u64 v[0:1], v[108:109], 1, v[0:1]
	s_addc_u32 s1, s21, s1
	v_mov_b32_e32 v36, v34
	v_lshl_add_u64 v[138:139], s[10:11], 0, v[0:1]
	v_lshl_add_u64 v[0:1], s[0:1], 0, v[32:33]
	v_readlane_b32 s8, v215, 22
	v_lshl_add_u64 v[0:1], v[36:37], 1, v[0:1]
	v_readlane_b32 s9, v215, 23
	v_mov_b32_e32 v42, v44
	v_mov_b32_e32 v177, 0
	v_lshl_add_u64 v[140:141], s[8:9], 0, v[0:1]
	v_lshl_add_u64 v[0:1], s[0:1], 0, v[40:41]
	v_lshl_add_u64 v[0:1], v[42:43], 1, v[0:1]
	v_lshl_add_u64 v[142:143], s[8:9], 0, v[0:1]
	v_lshl_add_u64 v[0:1], s[0:1], 0, v[50:51]
	v_lshl_add_u64 v[0:1], v[24:25], 1, v[0:1]
	v_ashrrev_i32_e32 v127, 31, v126
	v_cvt_pk_bf16_f32 v68, v28, v29
	v_cvt_pk_bf16_f32 v72, v20, v21
	v_cvt_pk_bf16_f32 v84, v16, v17
	v_cvt_pk_bf16_f32 v80, v12, v13
	v_cvt_pk_bf16_f32 v92, v8, v9
	v_lshl_add_u64 v[144:145], s[8:9], 0, v[0:1]
	s_mov_b32 s8, 0
	v_mov_b32_e32 v108, 0xf149f2ca
	v_mov_b32_e32 v16, 0
	v_mov_b32_e32 v17, v177
	v_mov_b32_e32 v18, v177
	v_mov_b32_e32 v19, v177
	v_mov_b32_e32 v20, v177
	v_mov_b32_e32 v21, v177
	v_mov_b32_e32 v22, v177
	v_mov_b32_e32 v23, v177
	v_mov_b32_e32 v24, v177
	v_mov_b32_e32 v25, v177
	v_mov_b32_e32 v26, v177
	v_mov_b32_e32 v27, v177
	v_mov_b32_e32 v28, v177
	v_mov_b32_e32 v29, v177
	v_mov_b32_e32 v30, v177
	v_mov_b32_e32 v31, v177
	v_mov_b32_e32 v0, 0
	v_mov_b32_e32 v1, v177
	v_mov_b32_e32 v2, v177
	v_mov_b32_e32 v3, v177
	v_mov_b32_e32 v4, v177
	v_mov_b32_e32 v5, v177
	v_mov_b32_e32 v6, v177
	v_mov_b32_e32 v7, v177
	v_mov_b32_e32 v8, v177
	v_mov_b32_e32 v9, v177
	v_mov_b32_e32 v10, v177
	v_mov_b32_e32 v11, v177
	v_mov_b32_e32 v12, v177
	v_mov_b32_e32 v13, v177
	v_mov_b32_e32 v14, v177
	v_mov_b32_e32 v15, v177
	s_waitcnt lgkmcnt(0)
	s_barrier
	v_readlane_b32 s37, v215, 7
	v_readlane_b32 s38, v215, 8
	v_readlane_b32 s39, v215, 9
	v_readlane_b32 s40, v215, 10
	v_readlane_b32 s41, v215, 11
	v_readlane_b32 s42, v215, 12
	v_readlane_b32 s43, v215, 13
	v_readlane_b32 s44, v215, 14
	v_readlane_b32 s45, v215, 15
	v_readlane_b32 s46, v215, 16
	v_readlane_b32 s47, v215, 17
	v_readlane_b32 s48, v215, 18
	v_readlane_b32 s49, v215, 19
	v_mov_b32_e32 v108, 0
	v_mov_b32_e32 v240, 0
	v_mov_b32_e32 v241, 0
	v_mov_b32_e32 v242, 0
	v_mov_b32_e32 v243, 0
	v_mov_b32_e32 v244, 0
	v_mov_b32_e32 v245, 0
	v_mov_b32_e32 v246, 0
	v_mov_b32_e32 v247, 0
	v_mov_b32_e32 v248, 0
	v_mov_b32_e32 v249, 0
	v_mov_b32_e32 v250, 0
	v_mov_b32_e32 v251, 0
	v_mov_b32_e32 v252, 0
	v_mov_b32_e32 v253, 0
	v_mov_b32_e32 v254, 0
	v_mov_b32_e32 v255, 0
	v_cndmask_b32_e64 v140, v134, v140, vcc
	v_cndmask_b32_e64 v141, v135, v141, vcc
	v_lshl_add_u64 v[140:141], v[140:141], 0, s[56:57]
	v_mov_b32_e32 v134, s34
	v_mov_b32_e32 v180, s76
	v_mov_b32_e32 v135, s35
	v_mov_b32_e32 v181, s77
	v_cndmask_b32_e64 v134, v134, v180, vcc
	v_cndmask_b32_e64 v135, v135, v181, vcc
	v_cndmask_b32_e64 v142, v136, v142, s[2:3]
	v_cndmask_b32_e64 v143, v137, v143, s[2:3]
	v_lshl_add_u64 v[142:143], v[142:143], 0, s[56:57]
	v_mov_b32_e32 v136, s34
	v_mov_b32_e32 v180, s76
	v_mov_b32_e32 v137, s35
	v_mov_b32_e32 v181, s77
	v_cndmask_b32_e64 v136, v136, v180, s[2:3]
	v_cndmask_b32_e64 v137, v137, v181, s[2:3]
	v_cndmask_b32_e64 v144, v138, v144, s[4:5]
	v_cndmask_b32_e64 v145, v139, v145, s[4:5]
	v_lshl_add_u64 v[144:145], v[144:145], 0, s[56:57]
	v_mov_b32_e32 v138, s34
	v_mov_b32_e32 v180, s76
	v_mov_b32_e32 v139, s35
	v_mov_b32_e32 v181, s77
	v_cndmask_b32_e64 v138, v138, v180, s[4:5]
	v_cndmask_b32_e64 v139, v139, v181, s[4:5]
	v_lshl_add_u64 v[130:131], v[130:131], 0, s[56:57]
	v_lshl_add_u64 v[132:133], v[132:133], 0, s[56:57]
.LBB0_917:
	s_bitcmp1_b32 s8, 0
	s_cselect_b32 s6, 0x5800, 0
	v_add_u32_e32 v32, s6, v176
	v_add_u32_e32 v173, v32, v128
	ds_read_b128 v[220:223], v173
	ds_read_b128 v[224:227], v173 offset:6656
	ds_read_b128 v[228:231], v173 offset:32
	ds_read_b128 v[232:235], v173 offset:6688
	ds_read_b128 v[236:239], v173 offset:64
	ds_read_b128 v[184:187], v173 offset:6720
	v_add_u32_e32 v174, s6, v175
	v_add_u32_e32 v174, v174, v122
	v_add_u32_e32 v172, 0x4000, v174
	v_add_u32_e32 v174, 0x3000, v174
	s_waitcnt lgkmcnt(5)
	v_mfma_f32_32x32x16_bf16 v[48:63], v[220:223], v[68:71], v[240:255]
	s_waitcnt lgkmcnt(4)
	v_mfma_f32_32x32x16_bf16 v[32:47], v[224:227], v[68:71], v[240:255]
	ds_read_b128 v[220:223], v173 offset:96
	ds_read_b128 v[224:227], v173 offset:6752
	s_waitcnt lgkmcnt(5)
	v_mfma_f32_32x32x16_bf16 v[48:63], v[228:231], v[72:75], v[48:63]
	s_waitcnt lgkmcnt(4)
	v_mfma_f32_32x32x16_bf16 v[32:47], v[232:235], v[72:75], v[32:47]
	ds_read_b128 v[228:231], v173 offset:128
	ds_read_b128 v[232:235], v173 offset:6784
	s_waitcnt lgkmcnt(5)
	v_mfma_f32_32x32x16_bf16 v[48:63], v[236:239], v[84:87], v[48:63]
	s_waitcnt lgkmcnt(4)
	v_mfma_f32_32x32x16_bf16 v[32:47], v[184:187], v[84:87], v[32:47]
	ds_read_b128 v[236:239], v173 offset:160
	ds_read_b128 v[184:187], v173 offset:6816
	s_waitcnt lgkmcnt(5)
	v_mfma_f32_32x32x16_bf16 v[48:63], v[220:223], v[80:83], v[48:63]
	s_waitcnt lgkmcnt(4)
	v_mfma_f32_32x32x16_bf16 v[32:47], v[224:227], v[80:83], v[32:47]
	ds_read2_b64 v[220:223], v174 offset0:128 offset1:130
	ds_read2_b64 v[224:227], v172 offset0:160 offset1:162
	s_waitcnt lgkmcnt(5)
	v_mfma_f32_32x32x16_bf16 v[48:63], v[228:231], v[92:95], v[48:63]
	s_waitcnt lgkmcnt(4)
	v_mfma_f32_32x32x16_bf16 v[32:47], v[232:235], v[92:95], v[32:47]
	ds_read2_b64 v[228:231], v174 offset0:132 offset1:134
	ds_read2_b64 v[232:235], v172 offset0:164 offset1:166
	s_waitcnt lgkmcnt(5)
	v_mfma_f32_32x32x16_bf16 v[48:63], v[236:239], v[88:91], v[48:63]
	s_waitcnt lgkmcnt(4)
	v_mfma_f32_32x32x16_bf16 v[32:47], v[184:187], v[88:91], v[32:47]
	ds_read2_b64 v[236:239], v174 offset0:136 offset1:138
	ds_read2_b64 v[184:187], v172 offset0:168 offset1:170
	s_add_i32 s8, s8, 1
	s_bitcmp1_b32 s8, 0
	s_cselect_b32 s0, 0x5800, 0
	v_add3_u32 v179, s0, v123, v125
	s_waitcnt vmcnt(4)
	ds_write_b128 v179, v[64:67]
	v_add3_u32 v179, s0, v129, v166
	s_waitcnt vmcnt(3)
	ds_write_b128 v179, v[76:79]
	v_add3_u32 v179, s0, v167, v168
	s_waitcnt vmcnt(2)
	ds_write_b128 v179, v[96:99]
	v_add_u32_e32 v179, s0, v169
	v_add3_u32 v179, v179, v124, s63
	s_waitcnt vmcnt(1)
	ds_write2_b64 v179, v[100:101], v[102:103] offset1:1
	v_add_u32_e32 v179, s0, v170
	v_add3_u32 v179, v179, v124, s63
	s_waitcnt vmcnt(0)
	ds_write2_b64 v179, v[104:105], v[106:107] offset1:1
	v_max3_f32 v188, v48, v49, v50
	v_max3_f32 v189, v32, v33, v34
	v_max3_f32 v188, v188, v51, v52
	v_max3_f32 v189, v189, v35, v36
	v_max3_f32 v188, v188, v53, v54
	v_max3_f32 v189, v189, v37, v38
	v_max3_f32 v188, v188, v55, v56
	v_max3_f32 v189, v189, v39, v40
	v_max3_f32 v188, v188, v57, v58
	v_max3_f32 v189, v189, v41, v42
	v_max3_f32 v188, v188, v59, v60
	v_max3_f32 v189, v189, v43, v44
	v_max3_f32 v188, v188, v61, v62
	v_max3_f32 v189, v189, v45, v46
	v_max3_f32 v188, v188, v63, v47
	v_max_f32_e32 v217, v188, v189
	v_cmp_lt_f32_e64 s[98:99], 4.0, v217
	global_load_dwordx4 v[64:67], v[140:141], off
	v_lshl_add_u64 v[140:141], v[140:141], 0, v[134:135]
	global_load_dwordx4 v[76:79], v[142:143], off
	v_lshl_add_u64 v[142:143], v[142:143], 0, v[136:137]
	global_load_dwordx4 v[96:99], v[144:145], off
	v_lshl_add_u64 v[144:145], v[144:145], 0, v[138:139]
	global_load_dwordx4 v[100:103], v[130:131], off offset:256
	v_lshl_add_u64 v[130:131], v[130:131], 0, s[12:13]
	global_load_dwordx4 v[104:107], v[132:133], off offset:256
	v_lshl_add_u64 v[132:133], v[132:133], 0, s[12:13]
	s_cmp_eq_u64 s[98:99], 0
	s_cbranch_scc0 .Lmla_slow
